# XCD-local barriers except after prep, after each mixer and after each layer's last phase (no cross-batch aliasing hazard can span a local barrier)
# baseline (speedup 1.0000x reference)
; DI unsigned xb_ld(unsigned* p)              { return __hip_atomic_load(p, __ATOMIC_RELAXED, __HIP_MEMORY_SCOPE_AGENT); }
; DI unsigned xb_add(unsigned* p, unsigned v) { return __hip_atomic_fetch_add(p, v, __ATOMIC_RELAXED, __HIP_MEMORY_SCOPE_AGENT); }
; #define XB_SPIN(cond, bar) do { unsigned _sp = 0; while (cond) { __builtin_amdgcn_s_sleep(1); \
;     if ((++_sp & 255u) == 0u) { if (xb_ld(&(bar)[XB_TMO])) break; if (_sp > XB_SPIN_CAP) { atomicAdd(&(bar)[XB_TMO], 1u); break; } } } } while (0)
; DI void xcd_barrier(const XcdBarrier& b, const int gw) {
;     ...
;         const unsigned old = xb_add(&bar[XB_XSUB(b.x)], 1u);
;         const unsigned gen = old / nloc;
;         if (old + 1u == (gen + 1u) * nloc) {
;             __builtin_amdgcn_fence(__ATOMIC_RELEASE, "agent");
;             asm volatile("s_waitcnt vmcnt(0)" ::: "memory");
;             const unsigned og = xb_add(&bar[XB_TOP], 1u);
;             const unsigned tg = og / nx;
;             if (og + 1u == (tg + 1u) * nx) xb_add(&bar[XB_TOPGEN], 1u);
;             else XB_SPIN(xb_ld(&bar[XB_TOPGEN]) == tg, bar);
;             __builtin_amdgcn_fence(__ATOMIC_ACQUIRE, "agent");
;             xb_add(&bar[XB_XGEN(b.x)], 1u);
.LBB0_528:
	s_andn2_saveexec_b64 s[8:9], s[8:9]
	s_cbranch_execz .LBB0_548
	s_mov_b64 s[8:9], exec
	s_add_i32 s98, s36, -1
	s_lshr_b32 s98, 0x1f5ebd7a, s98
	s_bitcmp1_b32 s98, 0
	s_cbranch_scc0 .Lxb_global
	v_mov_b32_e32 v1, 0x20048
	ds_read_b32 v1, v1
	s_waitcnt lgkmcnt(0)
	v_readfirstlane_b32 s98, v1
	s_cmp_lg_u32 s98, 0
	s_cbranch_scc1 .LBB0_545
